# attention item epilogue: 8 zb row loads hoisted and issued together, per-store vmcnt(0) drains replaced by counted vmcnt(7)
# baseline (speedup 1.0000x reference)
; #define LAS __attribute__((address_space(3)))
; #define SB_WAIT_V(n) asm volatile("s_waitcnt vmcnt(" #n ")" ::: "memory")
; #define SB_WAIT_L0() asm volatile("s_waitcnt lgkmcnt(0)" ::: "memory")
; __device__ __forceinline__ void sb_attn_item(bf16_t* PB, const bf16_t* VT, int b, int h, int qb, int lane, LAS unsigned char* wl  ) {
;     ...
;     SB_WAIT_V(0); SB_WAIT_L0();
; #pragma unroll
;     for (int blk = 0; blk < 4; ++blk)
; #pragma unroll
;         for (int g = 0; g < 4; ++g) { u32x2 w; w.x = cvtpk(o[blk][4 * g], o[blk][4 * g + 1]); w.y = cvtpk(o[blk][4 * g + 2], o[blk][4 * g + 3]);
;             *(LAS u32x2*)(kbuf + koff + (((4 * blk + g) ^ kx) << 4) + 8 * hi) = w; }
;     SB_WAIT_L0();
;     {
;         int ln = lane; asm volatile("" : "+v"(ln));
;         const size_t rowb = (size_t)(b * SEQ + qb * 32);
; #pragma unroll
;         for (int c = 0; c < 8; ++c) { const int r = 4 * c + (ln >> 4), chunk = (ln & 15) ^ (r & 15);
;             const u32x4 ov = *(const LAS u32x4*)(kbuf + c * 1024 + ln * 16);
;             bf16_t* rp = PB + (rowb + r) * PBW + h * 128 + chunk * 8;
;             const u32x4 zz = *(const u32x4*)(rp + C_ZB);
.LBB0_348:
	s_waitcnt vmcnt(0)
	s_nop 7
	v_cvt_pk_bf16_f32 v0, v0, v1
	v_cvt_pk_bf16_f32 v1, v2, v3
	v_add_u32_e32 v2, v151, v152
	s_waitcnt lgkmcnt(0)
	ds_write_b64 v2, v[0:1]
	v_cvt_pk_bf16_f32 v0, v4, v5
	v_cvt_pk_bf16_f32 v1, v6, v7
	ds_write_b64 v153, v[0:1]
	v_cvt_pk_bf16_f32 v0, v8, v9
	v_cvt_pk_bf16_f32 v1, v10, v11
	ds_write_b64 v154, v[0:1]
	v_cvt_pk_bf16_f32 v0, v12, v13
	v_cvt_pk_bf16_f32 v1, v14, v15
	ds_write_b64 v155, v[0:1]
	v_cvt_pk_bf16_f32 v0, v16, v17
	v_cvt_pk_bf16_f32 v1, v18, v19
	ds_write_b64 v156, v[0:1]
	v_cvt_pk_bf16_f32 v0, v20, v21
	v_cvt_pk_bf16_f32 v1, v22, v23
	ds_write_b64 v157, v[0:1]
	v_cvt_pk_bf16_f32 v0, v24, v25
	v_cvt_pk_bf16_f32 v1, v26, v27
	ds_write_b64 v158, v[0:1]
	v_cvt_pk_bf16_f32 v0, v28, v29
	v_cvt_pk_bf16_f32 v1, v30, v31
	ds_write_b64 v159, v[0:1]
	v_cvt_pk_bf16_f32 v0, v32, v33
	v_cvt_pk_bf16_f32 v1, v34, v35
	ds_write_b64 v160, v[0:1]
	v_cvt_pk_bf16_f32 v0, v36, v37
	v_cvt_pk_bf16_f32 v1, v38, v39
	ds_write_b64 v161, v[0:1]
	v_cvt_pk_bf16_f32 v0, v40, v41
	v_cvt_pk_bf16_f32 v1, v42, v43
	ds_write_b64 v162, v[0:1]
	v_cvt_pk_bf16_f32 v0, v44, v45
	v_cvt_pk_bf16_f32 v1, v46, v47
	ds_write_b64 v163, v[0:1]
	v_cvt_pk_bf16_f32 v0, v48, v49
	v_cvt_pk_bf16_f32 v1, v50, v51
	ds_write_b64 v164, v[0:1]
	v_cvt_pk_bf16_f32 v0, v52, v53
	v_cvt_pk_bf16_f32 v1, v54, v55
	s_lshl_b32 s33, s71, 5
	ds_write_b64 v166, v[0:1]
	v_cvt_pk_bf16_f32 v0, v56, v57
	v_cvt_pk_bf16_f32 v1, v58, v59
	ds_write_b64 v167, v[0:1]
	v_cvt_pk_bf16_f32 v0, v60, v61
	v_cvt_pk_bf16_f32 v1, v62, v63
	s_or_b32 s40, s33, s40
	ds_write_b64 v168, v[0:1]
	v_mov_b32_e32 v10, v150
	s_ashr_i32 s41, s40, 31
	s_waitcnt lgkmcnt(0)
	s_add_u32 s42, s92, s69
	v_ashrrev_i32_e32 v6, 4, v10
	s_addc_u32 s43, s93, 0
	v_ashrrev_i32_e32 v7, 31, v6
	v_xor_b32_e32 v8, v6, v10
	v_lshl_add_u64 v[0:1], v[6:7], 0, s[40:41]
	v_mov_b64_e32 v[4:5], s[42:43]
	v_mad_u64_u32 v[2:3], s[42:43], v0, s65, v[4:5]
	v_lshlrev_b32_e32 v0, 4, v8
	v_mad_i32_i24 v3, v1, s65, v3
	v_and_b32_e32 v194, 0xf0, v0
	v_lshl_add_u64 v[8:9], v[2:3], 0, v[194:195]
	v_mov_b32_e32 v98, 0x24000
	v_mov_b32_e32 v99, 0
	v_mov_b32_e32 v106, s72
	v_mov_b32_e32 v107, 0
	v_mov_b32_e32 v105, 0
	v_lshl_add_u64 v[100:101], v[2:3], 0, v[106:107]
	v_add_u32_e32 v96, 0, v6
	v_xor_b32_e32 v96, v96, v10
	v_lshlrev_b32_e32 v96, 4, v96
	v_and_b32_e32 v104, 0xf0, v96
	v_lshl_add_u64 v[108:109], v[100:101], 0, v[104:105]
	global_load_dwordx4 v[64:67], v[108:109], off
	v_lshl_add_u64 v[100:101], v[100:101], 0, v[98:99]
	v_add_u32_e32 v96, 4, v6
	v_xor_b32_e32 v96, v96, v10
	v_lshlrev_b32_e32 v96, 4, v96
	v_and_b32_e32 v104, 0xf0, v96
	v_lshl_add_u64 v[108:109], v[100:101], 0, v[104:105]
	global_load_dwordx4 v[68:71], v[108:109], off
	v_lshl_add_u64 v[100:101], v[100:101], 0, v[98:99]
	v_add_u32_e32 v96, 8, v6
	v_xor_b32_e32 v96, v96, v10
	v_lshlrev_b32_e32 v96, 4, v96
	v_and_b32_e32 v104, 0xf0, v96
	v_lshl_add_u64 v[108:109], v[100:101], 0, v[104:105]
	global_load_dwordx4 v[72:75], v[108:109], off
	v_lshl_add_u64 v[100:101], v[100:101], 0, v[98:99]
	v_add_u32_e32 v96, 12, v6
	v_xor_b32_e32 v96, v96, v10
	v_lshlrev_b32_e32 v96, 4, v96
	v_and_b32_e32 v104, 0xf0, v96
	v_lshl_add_u64 v[108:109], v[100:101], 0, v[104:105]
	global_load_dwordx4 v[76:79], v[108:109], off
	v_lshl_add_u64 v[100:101], v[100:101], 0, v[98:99]
	v_add_u32_e32 v96, 16, v6
	v_xor_b32_e32 v96, v96, v10
	v_lshlrev_b32_e32 v96, 4, v96
	v_and_b32_e32 v104, 0xf0, v96
	v_lshl_add_u64 v[108:109], v[100:101], 0, v[104:105]
	global_load_dwordx4 v[80:83], v[108:109], off
	v_lshl_add_u64 v[100:101], v[100:101], 0, v[98:99]
	v_add_u32_e32 v96, 20, v6
	v_xor_b32_e32 v96, v96, v10
	v_lshlrev_b32_e32 v96, 4, v96
	v_and_b32_e32 v104, 0xf0, v96
	v_lshl_add_u64 v[108:109], v[100:101], 0, v[104:105]
	global_load_dwordx4 v[84:87], v[108:109], off
	v_lshl_add_u64 v[100:101], v[100:101], 0, v[98:99]
	v_add_u32_e32 v96, 24, v6
	v_xor_b32_e32 v96, v96, v10
	v_lshlrev_b32_e32 v96, 4, v96
	v_and_b32_e32 v104, 0xf0, v96
	v_lshl_add_u64 v[108:109], v[100:101], 0, v[104:105]
	global_load_dwordx4 v[88:91], v[108:109], off
	v_lshl_add_u64 v[100:101], v[100:101], 0, v[98:99]
	v_add_u32_e32 v96, 28, v6
	v_xor_b32_e32 v96, v96, v10
	v_lshlrev_b32_e32 v96, 4, v96
	v_and_b32_e32 v104, 0xf0, v96
	v_lshl_add_u64 v[108:109], v[100:101], 0, v[104:105]
	global_load_dwordx4 v[92:95], v[108:109], off
	v_lshl_add_u64 v[100:101], v[100:101], 0, v[98:99]
	v_add_co_u32_e32 v0, vcc, s72, v8
	v_lshl_add_u32 v7, v10, 4, s86
	s_nop 0
	v_addc_co_u32_e32 v1, vcc, 0, v9, vcc
	ds_read_b128 v[16:19], v7
	ds_read_b128 v[0:3], v7 offset:1024
	v_add_co_u32_e32 v8, vcc, s1, v8
	s_add_i32 s50, s50, s74
	s_waitcnt lgkmcnt(0)
	v_lshlrev_b32_e32 v20, 16, v16
	v_and_b32_e32 v21, 0xffff0000, v16
	v_lshlrev_b32_e32 v16, 16, v17
	v_and_b32_e32 v17, 0xffff0000, v17
	v_addc_co_u32_e32 v9, vcc, 0, v9, vcc
	s_add_i32 s68, s68, s74
	s_add_i32 s56, s56, s82
	s_cmpk_gt_i32 s50, 0x1fff
	s_waitcnt vmcnt(7)
; #define LAS __attribute__((address_space(3)))
; __device__ __forceinline__ u32x4 pack8(const float (&f)[8]) { u32x4 w; w.x = cvtpk(f[0], f[1]); w.y = cvtpk(f[2], f[3]); w.z = cvtpk(f[4], f[5]); w.w = cvtpk(f[6], f[7]); return w; }
; __device__ __forceinline__ float fsigmoid(float v) { return __builtin_amdgcn_rcpf(1.f + __builtin_amdgcn_exp2f(-v * LOG2E)); }
; __device__ __forceinline__ void sb_attn_item(bf16_t* PB, const bf16_t* VT, int b, int h, int qb, int lane, LAS unsigned char* wl  ) {
;     ...
;         for (int c = 0; c < 8; ++c) { const int r = 4 * c + (ln >> 4), chunk = (ln & 15) ^ (r & 15);
;             const u32x4 ov = *(const LAS u32x4*)(kbuf + c * 1024 + ln * 16);
;             bf16_t* rp = PB + (rowb + r) * PBW + h * 128 + chunk * 8;
;             const u32x4 zz = *(const u32x4*)(rp + C_ZB);
;             float of[8], zf[8]; unpack8(ov, of); unpack8(zz, zf);
; #pragma unroll
;             for (int e = 0; e < 8; ++e) of[e] *= zf[e] * fsigmoid(zf[e]);
;             const u32x4 w = pack8(of);
;             *(u32x4*)(rp + C_Q) = w; }
	s_nop 1
	v_mov_b32_e32 v12, v64
	v_mov_b32_e32 v13, v65
	v_mov_b32_e32 v14, v66
	v_mov_b32_e32 v15, v67
	v_lshlrev_b32_e32 v22, 16, v12
	v_and_b32_e32 v23, 0xffff0000, v12
	v_lshlrev_b32_e32 v12, 16, v13
	v_mul_f32_e32 v11, 0xbfb8aa3b, v22
	v_mul_f32_e32 v24, 0xbfb8aa3b, v23
	v_and_b32_e32 v13, 0xffff0000, v13
	v_mul_f32_e32 v25, 0xbfb8aa3b, v12
	v_exp_f32_e32 v11, v11
	v_exp_f32_e32 v24, v24
	v_mul_f32_e32 v26, 0xbfb8aa3b, v13
	v_exp_f32_e32 v25, v25
	v_exp_f32_e32 v26, v26
	v_add_f32_e32 v11, 1.0, v11
	v_add_f32_e32 v27, 1.0, v24
	v_add_f32_e32 v28, 1.0, v25
	v_rcp_f32_e32 v24, v11
	v_rcp_f32_e32 v25, v27
	v_add_f32_e32 v29, 1.0, v26
	v_rcp_f32_e32 v26, v28
	v_rcp_f32_e32 v27, v29
	v_pk_mul_f32 v[22:23], v[24:25], v[22:23]
	v_pk_mul_f32 v[12:13], v[26:27], v[12:13]
	v_pk_mul_f32 v[20:21], v[22:23], v[20:21]
	v_lshlrev_b32_e32 v22, 16, v14
	v_and_b32_e32 v23, 0xffff0000, v14
	v_mul_f32_e32 v11, 0xbfb8aa3b, v22
	v_pk_mul_f32 v[16:17], v[12:13], v[16:17]
	v_exp_f32_e32 v11, v11
	v_mul_f32_e32 v13, 0xbfb8aa3b, v23
	v_exp_f32_e32 v14, v13
	v_lshlrev_b32_e32 v12, 16, v18
	v_add_f32_e32 v11, 1.0, v11
	v_rcp_f32_e32 v24, v11
	v_add_f32_e32 v11, 1.0, v14
	v_lshlrev_b32_e32 v14, 16, v15
	v_rcp_f32_e32 v25, v11
	v_and_b32_e32 v15, 0xffff0000, v15
	v_mul_f32_e32 v11, 0xbfb8aa3b, v14
	v_and_b32_e32 v13, 0xffff0000, v18
	v_exp_f32_e32 v11, v11
	v_mul_f32_e32 v18, 0xbfb8aa3b, v15
	v_exp_f32_e32 v18, v18
	v_pk_mul_f32 v[22:23], v[24:25], v[22:23]
	v_add_f32_e32 v11, 1.0, v11
	v_rcp_f32_e32 v24, v11
	v_add_f32_e32 v11, 1.0, v18
	v_rcp_f32_e32 v25, v11
	v_pk_mul_f32 v[22:23], v[22:23], v[12:13]
	v_lshlrev_b32_e32 v12, 16, v19
	v_and_b32_e32 v13, 0xffff0000, v19
	v_pk_mul_f32 v[14:15], v[24:25], v[14:15]
	s_nop 0
	v_pk_mul_f32 v[18:19], v[14:15], v[12:13]
	v_cvt_pk_bf16_f32 v12, v20, v21
	v_cvt_pk_bf16_f32 v13, v16, v17
	v_cvt_pk_bf16_f32 v14, v22, v23
	v_cvt_pk_bf16_f32 v15, v18, v19
	global_store_dwordx4 v[8:9], v[12:15], off
	v_add_u32_e32 v8, 4, v6
	v_ashrrev_i32_e32 v9, 31, v8
	v_xor_b32_e32 v11, v8, v10
	v_lshl_add_u64 v[8:9], v[8:9], 0, s[40:41]
	v_mad_u64_u32 v[12:13], s[42:43], v8, s65, v[4:5]
	v_lshlrev_b32_e32 v8, 4, v11
	v_mad_i32_i24 v13, v9, s65, v13
	v_and_b32_e32 v8, 0xf0, v8
	v_mov_b32_e32 v9, v195
	v_lshl_add_u64 v[8:9], v[12:13], 0, v[8:9]
	v_add_co_u32_e32 v12, vcc, s72, v8
	v_lshlrev_b32_e32 v18, 16, v2
	s_nop 0
	v_addc_co_u32_e32 v13, vcc, 0, v9, vcc
	v_and_b32_e32 v19, 0xffff0000, v2
	v_lshlrev_b32_e32 v16, 16, v0
	v_and_b32_e32 v17, 0xffff0000, v0
	v_lshlrev_b32_e32 v0, 16, v1
	v_and_b32_e32 v1, 0xffff0000, v1
	v_add_co_u32_e32 v8, vcc, s1, v8
	s_waitcnt vmcnt(7)
	s_nop 1
	v_mov_b32_e32 v12, v68
	v_mov_b32_e32 v13, v69
	v_mov_b32_e32 v14, v70
	v_mov_b32_e32 v15, v71
	v_lshlrev_b32_e32 v20, 16, v12
	v_and_b32_e32 v21, 0xffff0000, v12
	v_lshlrev_b32_e32 v12, 16, v13
	v_and_b32_e32 v13, 0xffff0000, v13
	v_lshlrev_b32_e32 v22, 16, v14
	v_and_b32_e32 v23, 0xffff0000, v14
	v_mul_f32_e32 v14, 0xbfb8aa3b, v12
	v_mul_f32_e32 v24, 0xbfb8aa3b, v13
	v_mul_f32_e32 v26, 0xbfb8aa3b, v23
	v_exp_f32_e32 v14, v14
	v_exp_f32_e32 v24, v24
	v_exp_f32_e32 v26, v26
	v_mul_f32_e32 v2, 0xbfb8aa3b, v20
	v_add_f32_e32 v14, 1.0, v14
	v_add_f32_e32 v27, 1.0, v24
	v_add_f32_e32 v29, 1.0, v26
	v_rcp_f32_e32 v26, v14
	v_rcp_f32_e32 v27, v27
	v_mul_f32_e32 v11, 0xbfb8aa3b, v21
	v_exp_f32_e32 v2, v2
	v_mul_f32_e32 v25, 0xbfb8aa3b, v22
	v_exp_f32_e32 v11, v11
	v_exp_f32_e32 v25, v25
	v_pk_mul_f32 v[12:13], v[26:27], v[12:13]
	v_add_f32_e32 v2, 1.0, v2
	v_pk_mul_f32 v[12:13], v[12:13], v[0:1]
	v_lshlrev_b32_e32 v0, 16, v15
	v_add_f32_e32 v11, 1.0, v11
	v_rcp_f32_e32 v24, v2
	v_and_b32_e32 v1, 0xffff0000, v15
	v_mul_f32_e32 v2, 0xbfb8aa3b, v0
	v_add_f32_e32 v28, 1.0, v25
	v_rcp_f32_e32 v25, v11
	v_exp_f32_e32 v2, v2
	v_mul_f32_e32 v11, 0xbfb8aa3b, v1
	v_exp_f32_e32 v11, v11
	v_pk_mul_f32 v[20:21], v[24:25], v[20:21]
	v_add_f32_e32 v2, 1.0, v2
	v_pk_mul_f32 v[16:17], v[20:21], v[16:17]
	v_rcp_f32_e32 v20, v2
	v_add_f32_e32 v2, 1.0, v11
	v_rcp_f32_e32 v28, v28
	v_rcp_f32_e32 v29, v29
	v_rcp_f32_e32 v21, v2
	v_lshlrev_b32_e32 v2, 16, v3
	v_and_b32_e32 v3, 0xffff0000, v3
	v_pk_mul_f32 v[14:15], v[28:29], v[22:23]
	v_pk_mul_f32 v[0:1], v[20:21], v[0:1]
	v_pk_mul_f32 v[14:15], v[14:15], v[18:19]
	v_pk_mul_f32 v[18:19], v[0:1], v[2:3]
	v_cvt_pk_bf16_f32 v0, v16, v17
	v_cvt_pk_bf16_f32 v1, v12, v13
	v_cvt_pk_bf16_f32 v2, v14, v15
	v_cvt_pk_bf16_f32 v3, v18, v19
	v_addc_co_u32_e32 v9, vcc, 0, v9, vcc
	global_store_dwordx4 v[8:9], v[0:3], off
	s_nop 1
	v_add_u32_e32 v0, 8, v6
	v_ashrrev_i32_e32 v1, 31, v0
	v_xor_b32_e32 v8, v0, v10
	v_lshl_add_u64 v[0:1], v[0:1], 0, s[40:41]
	v_mad_u64_u32 v[2:3], s[42:43], v0, s65, v[4:5]
	v_lshlrev_b32_e32 v0, 4, v8
	v_mad_i32_i24 v3, v1, s65, v3
	v_and_b32_e32 v0, 0xf0, v0
	v_mov_b32_e32 v1, v195
	v_lshl_add_u64 v[8:9], v[2:3], 0, v[0:1]
	v_add_co_u32_e32 v0, vcc, s72, v8
	s_nop 1
	v_addc_co_u32_e32 v1, vcc, 0, v9, vcc
	ds_read_b128 v[16:19], v7 offset:2048
	ds_read_b128 v[0:3], v7 offset:3072
	v_add_co_u32_e32 v8, vcc, s1, v8
	s_waitcnt lgkmcnt(1)
	v_lshlrev_b32_e32 v22, 16, v18
	v_and_b32_e32 v23, 0xffff0000, v18
	v_lshlrev_b32_e32 v20, 16, v16
	v_and_b32_e32 v21, 0xffff0000, v16
	v_lshlrev_b32_e32 v16, 16, v17
	v_and_b32_e32 v17, 0xffff0000, v17
	v_addc_co_u32_e32 v9, vcc, 0, v9, vcc
	s_waitcnt vmcnt(7)
; #define LAS __attribute__((address_space(3)))
; __device__ __forceinline__ float fsigmoid(float v) { return __builtin_amdgcn_rcpf(1.f + __builtin_amdgcn_exp2f(-v * LOG2E)); }
; __device__ __forceinline__ u32x4 pack8(const float (&f)[8]) { u32x4 w; w.x = cvtpk(f[0], f[1]); w.y = cvtpk(f[2], f[3]); w.z = cvtpk(f[4], f[5]); w.w = cvtpk(f[6], f[7]); return w; }
; __device__ __forceinline__ void sb_attn_item(bf16_t* PB, const bf16_t* VT, int b, int h, int qb, int lane, LAS unsigned char* wl  ) {
;     ...
;         for (int c = 0; c < 8; ++c) { const int r = 4 * c + (ln >> 4), chunk = (ln & 15) ^ (r & 15);
;             const u32x4 ov = *(const LAS u32x4*)(kbuf + c * 1024 + ln * 16);
;             bf16_t* rp = PB + (rowb + r) * PBW + h * 128 + chunk * 8;
;             const u32x4 zz = *(const u32x4*)(rp + C_ZB);
;             float of[8], zf[8]; unpack8(ov, of); unpack8(zz, zf);
; #pragma unroll
;             for (int e = 0; e < 8; ++e) of[e] *= zf[e] * fsigmoid(zf[e]);
;             const u32x4 w = pack8(of);
;             *(u32x4*)(rp + C_Q) = w; }
	s_nop 1
	v_mov_b32_e32 v12, v72
	v_mov_b32_e32 v13, v73
	v_mov_b32_e32 v14, v74
	v_mov_b32_e32 v15, v75
	v_lshlrev_b32_e32 v24, 16, v12
	v_and_b32_e32 v25, 0xffff0000, v12
	v_lshlrev_b32_e32 v12, 16, v13
	v_and_b32_e32 v13, 0xffff0000, v13
	v_lshlrev_b32_e32 v26, 16, v14
	v_and_b32_e32 v27, 0xffff0000, v14
	v_lshlrev_b32_e32 v14, 16, v15
	v_and_b32_e32 v15, 0xffff0000, v15
	v_mul_f32_e32 v28, 0xbfb8aa3b, v12
	v_mul_f32_e32 v29, 0xbfb8aa3b, v13
	v_mul_f32_e32 v11, 0xbfb8aa3b, v24
	v_mul_f32_e32 v18, 0xbfb8aa3b, v25
	v_mul_f32_e32 v30, 0xbfb8aa3b, v26
	v_mul_f32_e32 v31, 0xbfb8aa3b, v27
	v_mul_f32_e32 v32, 0xbfb8aa3b, v14
	v_mul_f32_e32 v33, 0xbfb8aa3b, v15
	v_exp_f32_e32 v28, v28
	v_exp_f32_e32 v29, v29
	v_exp_f32_e32 v11, v11
	v_exp_f32_e32 v18, v18
	v_exp_f32_e32 v30, v30
	v_exp_f32_e32 v31, v31
	v_exp_f32_e32 v32, v32
	v_exp_f32_e32 v33, v33
	v_add_f32_e32 v34, 1.0, v28
	v_add_f32_e32 v35, 1.0, v29
	v_add_f32_e32 v11, 1.0, v11
	v_add_f32_e32 v18, 1.0, v18
	v_add_f32_e32 v36, 1.0, v30
	v_add_f32_e32 v37, 1.0, v31
	v_add_f32_e32 v38, 1.0, v32
	v_add_f32_e32 v39, 1.0, v33
	v_rcp_f32_e32 v30, v34
	v_rcp_f32_e32 v31, v35
	v_rcp_f32_e32 v28, v11
	v_rcp_f32_e32 v29, v18
	v_rcp_f32_e32 v32, v36
	v_rcp_f32_e32 v33, v37
	v_rcp_f32_e32 v34, v38
	v_rcp_f32_e32 v35, v39
	v_pk_mul_f32 v[12:13], v[30:31], v[12:13]
	v_pk_mul_f32 v[24:25], v[28:29], v[24:25]
	v_pk_mul_f32 v[26:27], v[32:33], v[26:27]
	v_pk_mul_f32 v[16:17], v[12:13], v[16:17]
	v_lshlrev_b32_e32 v12, 16, v19
	v_and_b32_e32 v13, 0xffff0000, v19
	v_pk_mul_f32 v[14:15], v[34:35], v[14:15]
	v_pk_mul_f32 v[20:21], v[24:25], v[20:21]
	v_pk_mul_f32 v[22:23], v[26:27], v[22:23]
	v_pk_mul_f32 v[18:19], v[14:15], v[12:13]
	v_cvt_pk_bf16_f32 v12, v20, v21
	v_cvt_pk_bf16_f32 v13, v16, v17
	v_cvt_pk_bf16_f32 v14, v22, v23
	v_cvt_pk_bf16_f32 v15, v18, v19
	global_store_dwordx4 v[8:9], v[12:15], off
	v_add_u32_e32 v8, 12, v6
	v_ashrrev_i32_e32 v9, 31, v8
	v_xor_b32_e32 v11, v8, v10
	v_lshl_add_u64 v[8:9], v[8:9], 0, s[40:41]
	v_mad_u64_u32 v[12:13], s[42:43], v8, s65, v[4:5]
	v_lshlrev_b32_e32 v8, 4, v11
	v_mad_i32_i24 v13, v9, s65, v13
	v_and_b32_e32 v8, 0xf0, v8
	v_mov_b32_e32 v9, v195
	v_lshl_add_u64 v[8:9], v[12:13], 0, v[8:9]
	v_add_co_u32_e32 v12, vcc, s72, v8
	v_add_u32_e32 v16, 16, v6
	s_nop 0
	v_addc_co_u32_e32 v13, vcc, 0, v9, vcc
	s_waitcnt lgkmcnt(0)
	v_lshlrev_b32_e32 v18, 16, v0
	v_and_b32_e32 v19, 0xffff0000, v0
	v_lshlrev_b32_e32 v0, 16, v1
	v_and_b32_e32 v1, 0xffff0000, v1
	v_lshlrev_b32_e32 v20, 16, v2
	v_and_b32_e32 v21, 0xffff0000, v2
	v_lshlrev_b32_e32 v2, 16, v3
	v_and_b32_e32 v3, 0xffff0000, v3
	v_ashrrev_i32_e32 v17, 31, v16
	v_add_co_u32_e32 v8, vcc, s1, v8
	v_lshl_add_u64 v[16:17], v[16:17], 0, s[40:41]
	s_nop 0
	v_addc_co_u32_e32 v9, vcc, 0, v9, vcc
	s_waitcnt vmcnt(7)
	s_nop 1
	v_mov_b32_e32 v12, v76
	v_mov_b32_e32 v13, v77
	v_mov_b32_e32 v14, v78
	v_mov_b32_e32 v15, v79
	v_lshlrev_b32_e32 v22, 16, v12
	v_and_b32_e32 v23, 0xffff0000, v12
	v_lshlrev_b32_e32 v12, 16, v13
	v_and_b32_e32 v13, 0xffff0000, v13
	v_lshlrev_b32_e32 v24, 16, v14
	v_and_b32_e32 v25, 0xffff0000, v14
	v_lshlrev_b32_e32 v14, 16, v15
	v_and_b32_e32 v15, 0xffff0000, v15
	v_mul_f32_e32 v11, 0xbfb8aa3b, v22
	v_mul_f32_e32 v26, 0xbfb8aa3b, v23
	v_mul_f32_e32 v27, 0xbfb8aa3b, v12
	v_mul_f32_e32 v28, 0xbfb8aa3b, v13
	v_mul_f32_e32 v29, 0xbfb8aa3b, v24
	v_mul_f32_e32 v30, 0xbfb8aa3b, v25
	v_mul_f32_e32 v31, 0xbfb8aa3b, v14
	v_mul_f32_e32 v32, 0xbfb8aa3b, v15
	v_exp_f32_e32 v11, v11
	v_exp_f32_e32 v26, v26
	v_exp_f32_e32 v27, v27
	v_exp_f32_e32 v28, v28
	v_exp_f32_e32 v29, v29
	v_exp_f32_e32 v30, v30
	v_exp_f32_e32 v31, v31
	v_exp_f32_e32 v32, v32
	v_add_f32_e32 v11, 1.0, v11
	v_add_f32_e32 v33, 1.0, v26
	v_add_f32_e32 v34, 1.0, v27
	v_add_f32_e32 v35, 1.0, v28
	v_add_f32_e32 v36, 1.0, v29
	v_add_f32_e32 v37, 1.0, v30
	v_add_f32_e32 v38, 1.0, v31
	v_add_f32_e32 v39, 1.0, v32
	v_rcp_f32_e32 v26, v11
	v_rcp_f32_e32 v27, v33
	v_rcp_f32_e32 v28, v34
	v_rcp_f32_e32 v29, v35
	v_rcp_f32_e32 v30, v36
	v_rcp_f32_e32 v31, v37
	v_rcp_f32_e32 v32, v38
	v_rcp_f32_e32 v33, v39
	v_pk_mul_f32 v[22:23], v[26:27], v[22:23]
	v_pk_mul_f32 v[12:13], v[28:29], v[12:13]
	v_pk_mul_f32 v[24:25], v[30:31], v[24:25]
	v_pk_mul_f32 v[14:15], v[32:33], v[14:15]
	v_pk_mul_f32 v[18:19], v[22:23], v[18:19]
	v_pk_mul_f32 v[12:13], v[12:13], v[0:1]
	v_pk_mul_f32 v[20:21], v[24:25], v[20:21]
	v_pk_mul_f32 v[14:15], v[14:15], v[2:3]
	v_cvt_pk_bf16_f32 v0, v18, v19
	v_cvt_pk_bf16_f32 v1, v12, v13
	v_cvt_pk_bf16_f32 v2, v20, v21
	v_cvt_pk_bf16_f32 v3, v14, v15
	global_store_dwordx4 v[8:9], v[0:3], off
	v_add_u32_e32 v20, 20, v6
	v_xor_b32_e32 v11, v20, v10
	v_mad_u64_u32 v[0:1], s[42:43], v16, s65, v[4:5]
	v_mad_i32_i24 v1, v17, s65, v1
	v_lshl_add_u64 v[8:9], v[0:1], 0, v[194:195]
	v_add_co_u32_e32 v0, vcc, s72, v8
	v_lshlrev_b32_e32 v11, 4, v11
	s_nop 0
	v_addc_co_u32_e32 v1, vcc, 0, v9, vcc
	v_and_b32_e32 v194, 0xf0, v11
	ds_read_b128 v[12:15], v7 offset:4096
	ds_read_b128 v[16:19], v7 offset:5120
	v_ashrrev_i32_e32 v21, 31, v20
	v_lshl_add_u64 v[20:21], v[20:21], 0, s[40:41]
	v_mad_u64_u32 v[22:23], s[42:43], v20, s65, v[4:5]
	v_mad_i32_i24 v23, v21, s65, v23
	s_waitcnt lgkmcnt(1)
	v_lshlrev_b32_e32 v20, 16, v12
	v_and_b32_e32 v21, 0xffff0000, v12
	v_lshlrev_b32_e32 v12, 16, v13
	v_and_b32_e32 v13, 0xffff0000, v13
	v_lshlrev_b32_e32 v24, 16, v14
	v_and_b32_e32 v25, 0xffff0000, v14
	v_lshlrev_b32_e32 v14, 16, v15
	v_and_b32_e32 v15, 0xffff0000, v15
	v_add_co_u32_e32 v8, vcc, s1, v8
	v_lshl_add_u64 v[22:23], v[22:23], 0, v[194:195]
	s_nop 0
	v_addc_co_u32_e32 v9, vcc, 0, v9, vcc
	v_add_co_u32_e32 v26, vcc, s72, v22
	s_waitcnt vmcnt(7)
; #define LAS __attribute__((address_space(3)))
; __device__ __forceinline__ float fsigmoid(float v) { return __builtin_amdgcn_rcpf(1.f + __builtin_amdgcn_exp2f(-v * LOG2E)); }
; __device__ __forceinline__ u32x4 pack8(const float (&f)[8]) { u32x4 w; w.x = cvtpk(f[0], f[1]); w.y = cvtpk(f[2], f[3]); w.z = cvtpk(f[4], f[5]); w.w = cvtpk(f[6], f[7]); return w; }
; __device__ __forceinline__ void sb_attn_item(bf16_t* PB, const bf16_t* VT, int b, int h, int qb, int lane, LAS unsigned char* wl  ) {
;     ...
;         for (int c = 0; c < 8; ++c) { const int r = 4 * c + (ln >> 4), chunk = (ln & 15) ^ (r & 15);
;             const u32x4 ov = *(const LAS u32x4*)(kbuf + c * 1024 + ln * 16);
;             bf16_t* rp = PB + (rowb + r) * PBW + h * 128 + chunk * 8;
;             const u32x4 zz = *(const u32x4*)(rp + C_ZB);
;             float of[8], zf[8]; unpack8(ov, of); unpack8(zz, zf);
; #pragma unroll
;             for (int e = 0; e < 8; ++e) of[e] *= zf[e] * fsigmoid(zf[e]);
;             const u32x4 w = pack8(of);
;             *(u32x4*)(rp + C_Q) = w; }
	s_nop 1
	v_mov_b32_e32 v0, v80
	v_mov_b32_e32 v1, v81
	v_mov_b32_e32 v2, v82
	v_mov_b32_e32 v3, v83
	v_lshlrev_b32_e32 v28, 16, v0
	v_and_b32_e32 v29, 0xffff0000, v0
	v_lshlrev_b32_e32 v0, 16, v1
	v_and_b32_e32 v1, 0xffff0000, v1
	v_lshlrev_b32_e32 v30, 16, v2
	v_and_b32_e32 v31, 0xffff0000, v2
	v_lshlrev_b32_e32 v2, 16, v3
	v_and_b32_e32 v3, 0xffff0000, v3
	v_mul_f32_e32 v11, 0xbfb8aa3b, v28
	v_mul_f32_e32 v32, 0xbfb8aa3b, v29
	v_mul_f32_e32 v33, 0xbfb8aa3b, v0
	v_mul_f32_e32 v34, 0xbfb8aa3b, v1
	v_mul_f32_e32 v35, 0xbfb8aa3b, v30
	v_mul_f32_e32 v36, 0xbfb8aa3b, v31
	v_mul_f32_e32 v37, 0xbfb8aa3b, v2
	v_mul_f32_e32 v38, 0xbfb8aa3b, v3
	v_exp_f32_e32 v11, v11
	v_exp_f32_e32 v32, v32
	v_exp_f32_e32 v33, v33
	v_exp_f32_e32 v34, v34
	v_exp_f32_e32 v35, v35
	v_exp_f32_e32 v36, v36
	v_exp_f32_e32 v37, v37
	v_exp_f32_e32 v38, v38
	v_add_f32_e32 v11, 1.0, v11
	v_add_f32_e32 v39, 1.0, v32
	v_add_f32_e32 v40, 1.0, v33
	v_add_f32_e32 v41, 1.0, v34
	v_add_f32_e32 v42, 1.0, v35
	v_add_f32_e32 v43, 1.0, v36
	v_add_f32_e32 v44, 1.0, v37
	v_add_f32_e32 v45, 1.0, v38
	v_rcp_f32_e32 v32, v11
	v_rcp_f32_e32 v33, v39
	v_rcp_f32_e32 v34, v40
	v_rcp_f32_e32 v35, v41
	v_rcp_f32_e32 v36, v42
	v_rcp_f32_e32 v37, v43
	v_rcp_f32_e32 v38, v44
	v_rcp_f32_e32 v39, v45
	v_pk_mul_f32 v[28:29], v[32:33], v[28:29]
	v_pk_mul_f32 v[0:1], v[34:35], v[0:1]
	v_pk_mul_f32 v[30:31], v[36:37], v[30:31]
	v_pk_mul_f32 v[2:3], v[38:39], v[2:3]
	v_pk_mul_f32 v[20:21], v[28:29], v[20:21]
	v_pk_mul_f32 v[12:13], v[0:1], v[12:13]
	v_pk_mul_f32 v[24:25], v[30:31], v[24:25]
	v_pk_mul_f32 v[14:15], v[2:3], v[14:15]
	v_cvt_pk_bf16_f32 v0, v20, v21
	v_cvt_pk_bf16_f32 v1, v12, v13
	v_cvt_pk_bf16_f32 v2, v24, v25
	v_cvt_pk_bf16_f32 v3, v14, v15
	v_addc_co_u32_e32 v27, vcc, 0, v23, vcc
	global_store_dwordx4 v[8:9], v[0:3], off
	v_add_u32_e32 v8, 24, v6
	v_xor_b32_e32 v11, v8, v10
	v_lshlrev_b32_e32 v11, 4, v11
	v_and_b32_e32 v194, 0xf0, v11
	v_ashrrev_i32_e32 v9, 31, v8
	v_lshl_add_u64 v[8:9], v[8:9], 0, s[40:41]
	v_mad_u64_u32 v[12:13], s[42:43], v8, s65, v[4:5]
	v_mad_i32_i24 v13, v9, s65, v13
	s_waitcnt lgkmcnt(0)
	v_lshlrev_b32_e32 v8, 16, v16
	v_and_b32_e32 v9, 0xffff0000, v16
	v_lshlrev_b32_e32 v14, 16, v17
	v_and_b32_e32 v15, 0xffff0000, v17
	v_lshlrev_b32_e32 v16, 16, v18
	v_and_b32_e32 v17, 0xffff0000, v18
	v_lshlrev_b32_e32 v18, 16, v19
	v_and_b32_e32 v19, 0xffff0000, v19
	v_add_co_u32_e32 v20, vcc, s1, v22
	s_waitcnt vmcnt(7)
	s_nop 1
	v_mov_b32_e32 v0, v84
	v_mov_b32_e32 v1, v85
	v_mov_b32_e32 v2, v86
	v_mov_b32_e32 v3, v87
	v_lshlrev_b32_e32 v24, 16, v0
	v_and_b32_e32 v25, 0xffff0000, v0
	v_lshlrev_b32_e32 v0, 16, v1
	v_and_b32_e32 v1, 0xffff0000, v1
	v_lshlrev_b32_e32 v26, 16, v2
	v_and_b32_e32 v27, 0xffff0000, v2
	v_lshlrev_b32_e32 v2, 16, v3
	v_and_b32_e32 v3, 0xffff0000, v3
	v_mul_f32_e32 v11, 0xbfb8aa3b, v24
	v_mul_f32_e32 v28, 0xbfb8aa3b, v25
	v_mul_f32_e32 v29, 0xbfb8aa3b, v0
	v_mul_f32_e32 v30, 0xbfb8aa3b, v1
	v_mul_f32_e32 v31, 0xbfb8aa3b, v26
	v_mul_f32_e32 v32, 0xbfb8aa3b, v27
	v_mul_f32_e32 v33, 0xbfb8aa3b, v2
	v_mul_f32_e32 v34, 0xbfb8aa3b, v3
	v_exp_f32_e32 v11, v11
	v_exp_f32_e32 v28, v28
	v_exp_f32_e32 v29, v29
	v_exp_f32_e32 v30, v30
	v_exp_f32_e32 v31, v31
	v_exp_f32_e32 v32, v32
	v_exp_f32_e32 v33, v33
	v_exp_f32_e32 v34, v34
	v_add_f32_e32 v11, 1.0, v11
	v_add_f32_e32 v35, 1.0, v28
	v_add_f32_e32 v36, 1.0, v29
	v_add_f32_e32 v37, 1.0, v30
	v_add_f32_e32 v38, 1.0, v31
	v_add_f32_e32 v39, 1.0, v32
	v_add_f32_e32 v40, 1.0, v33
	v_add_f32_e32 v41, 1.0, v34
	v_rcp_f32_e32 v28, v11
	v_rcp_f32_e32 v29, v35
	v_rcp_f32_e32 v30, v36
	v_rcp_f32_e32 v31, v37
	v_rcp_f32_e32 v32, v38
	v_rcp_f32_e32 v33, v39
	v_rcp_f32_e32 v34, v40
	v_rcp_f32_e32 v35, v41
	v_pk_mul_f32 v[24:25], v[28:29], v[24:25]
	v_pk_mul_f32 v[0:1], v[30:31], v[0:1]
	v_pk_mul_f32 v[26:27], v[32:33], v[26:27]
	v_pk_mul_f32 v[2:3], v[34:35], v[2:3]
	v_addc_co_u32_e32 v21, vcc, 0, v23, vcc
	v_lshl_add_u64 v[22:23], v[12:13], 0, v[194:195]
	v_pk_mul_f32 v[8:9], v[24:25], v[8:9]
	v_pk_mul_f32 v[14:15], v[0:1], v[14:15]
	v_pk_mul_f32 v[16:17], v[26:27], v[16:17]
	v_pk_mul_f32 v[18:19], v[2:3], v[18:19]
	v_add_co_u32_e32 v12, vcc, s72, v22
	v_cvt_pk_bf16_f32 v0, v8, v9
	v_cvt_pk_bf16_f32 v1, v14, v15
	v_cvt_pk_bf16_f32 v2, v16, v17
	v_cvt_pk_bf16_f32 v3, v18, v19
	v_addc_co_u32_e32 v13, vcc, 0, v23, vcc
	global_store_dwordx4 v[20:21], v[0:3], off
	v_add_u32_e32 v16, 28, v6
	v_xor_b32_e32 v18, v16, v10
	v_lshlrev_b32_e32 v18, 4, v18
	v_and_b32_e32 v194, 0xf0, v18
	v_add_co_u32_e32 v18, vcc, s1, v22
	ds_read_b128 v[12:15], v7 offset:6144
	ds_read_b128 v[6:9], v7 offset:7168
	v_addc_co_u32_e32 v19, vcc, 0, v23, vcc
	v_ashrrev_i32_e32 v17, 31, v16
	v_lshl_add_u64 v[10:11], v[16:17], 0, s[40:41]
	v_mad_u64_u32 v[4:5], s[40:41], v10, s65, v[4:5]
	v_mad_i32_i24 v5, v11, s65, v5
	s_waitcnt lgkmcnt(1)
; #define LAS __attribute__((address_space(3)))
; __device__ __forceinline__ float fsigmoid(float v) { return __builtin_amdgcn_rcpf(1.f + __builtin_amdgcn_exp2f(-v * LOG2E)); }
; __device__ __forceinline__ u32x4 pack8(const float (&f)[8]) { u32x4 w; w.x = cvtpk(f[0], f[1]); w.y = cvtpk(f[2], f[3]); w.z = cvtpk(f[4], f[5]); w.w = cvtpk(f[6], f[7]); return w; }
; __device__ __forceinline__ void sb_attn_item(bf16_t* PB, const bf16_t* VT, int b, int h, int qb, int lane, LAS unsigned char* wl  ) {
;     ...
;         for (int c = 0; c < 8; ++c) { const int r = 4 * c + (ln >> 4), chunk = (ln & 15) ^ (r & 15);
;             const u32x4 ov = *(const LAS u32x4*)(kbuf + c * 1024 + ln * 16);
;             bf16_t* rp = PB + (rowb + r) * PBW + h * 128 + chunk * 8;
;             const u32x4 zz = *(const u32x4*)(rp + C_ZB);
;             float of[8], zf[8]; unpack8(ov, of); unpack8(zz, zf);
; #pragma unroll
;             for (int e = 0; e < 8; ++e) of[e] *= zf[e] * fsigmoid(zf[e]);
;             const u32x4 w = pack8(of);
;             *(u32x4*)(rp + C_Q) = w; }
; __device__ __forceinline__ void phase_mixers(PP p, int l, int lane, int wave, LAS unsigned char* lds) {
;     ...
;     for (int item = gwa; item < NBATCH * 16 * 128; item += NGW) { const int bh = item >> 7, qb = item & 127; sb_attn_item(PB, VT, bh >> 4, bh & 15, qb, lane, lds + wave * 16384); }
	v_lshlrev_b32_e32 v10, 16, v12
	v_and_b32_e32 v11, 0xffff0000, v12
	v_lshlrev_b32_e32 v12, 16, v13
	v_and_b32_e32 v13, 0xffff0000, v13
	v_lshlrev_b32_e32 v16, 16, v14
	v_and_b32_e32 v17, 0xffff0000, v14
	v_lshlrev_b32_e32 v14, 16, v15
	v_and_b32_e32 v15, 0xffff0000, v15
	v_lshl_add_u64 v[4:5], v[4:5], 0, v[194:195]
	v_add_co_u32_e32 v20, vcc, s72, v4
	s_waitcnt vmcnt(7)
	s_nop 1
	v_mov_b32_e32 v0, v88
	v_mov_b32_e32 v1, v89
	v_mov_b32_e32 v2, v90
	v_mov_b32_e32 v3, v91
	v_lshlrev_b32_e32 v22, 16, v0
	v_and_b32_e32 v23, 0xffff0000, v0
	v_lshlrev_b32_e32 v0, 16, v1
	v_and_b32_e32 v1, 0xffff0000, v1
	v_lshlrev_b32_e32 v24, 16, v2
	v_and_b32_e32 v25, 0xffff0000, v2
	v_lshlrev_b32_e32 v2, 16, v3
	v_and_b32_e32 v3, 0xffff0000, v3
	v_mul_f32_e32 v26, 0xbfb8aa3b, v22
	v_mul_f32_e32 v27, 0xbfb8aa3b, v23
	v_mul_f32_e32 v28, 0xbfb8aa3b, v0
	v_mul_f32_e32 v29, 0xbfb8aa3b, v1
	v_mul_f32_e32 v30, 0xbfb8aa3b, v24
	v_mul_f32_e32 v31, 0xbfb8aa3b, v25
	v_mul_f32_e32 v32, 0xbfb8aa3b, v2
	v_mul_f32_e32 v33, 0xbfb8aa3b, v3
	v_exp_f32_e32 v26, v26
	v_exp_f32_e32 v27, v27
	v_exp_f32_e32 v28, v28
	v_exp_f32_e32 v29, v29
	v_exp_f32_e32 v30, v30
	v_exp_f32_e32 v31, v31
	v_exp_f32_e32 v32, v32
	v_exp_f32_e32 v33, v33
	v_add_f32_e32 v26, 1.0, v26
	v_add_f32_e32 v27, 1.0, v27
	v_add_f32_e32 v28, 1.0, v28
	v_add_f32_e32 v29, 1.0, v29
	v_add_f32_e32 v30, 1.0, v30
	v_add_f32_e32 v31, 1.0, v31
	v_add_f32_e32 v32, 1.0, v32
	v_add_f32_e32 v33, 1.0, v33
	v_rcp_f32_e32 v26, v26
	v_rcp_f32_e32 v27, v27
	v_rcp_f32_e32 v28, v28
	v_rcp_f32_e32 v29, v29
	v_rcp_f32_e32 v30, v30
	v_rcp_f32_e32 v31, v31
	v_rcp_f32_e32 v32, v32
	v_rcp_f32_e32 v33, v33
	v_pk_mul_f32 v[22:23], v[26:27], v[22:23]
	v_pk_mul_f32 v[0:1], v[28:29], v[0:1]
	v_pk_mul_f32 v[24:25], v[30:31], v[24:25]
	v_pk_mul_f32 v[2:3], v[32:33], v[2:3]
	v_pk_mul_f32 v[10:11], v[22:23], v[10:11]
	v_pk_mul_f32 v[12:13], v[0:1], v[12:13]
	v_pk_mul_f32 v[16:17], v[24:25], v[16:17]
	v_pk_mul_f32 v[14:15], v[2:3], v[14:15]
	v_cvt_pk_bf16_f32 v0, v10, v11
	v_cvt_pk_bf16_f32 v1, v12, v13
	v_cvt_pk_bf16_f32 v2, v16, v17
	v_cvt_pk_bf16_f32 v3, v14, v15
	v_addc_co_u32_e32 v21, vcc, 0, v5, vcc
	global_store_dwordx4 v[18:19], v[0:3], off
	s_waitcnt lgkmcnt(0)
	v_lshlrev_b32_e32 v10, 16, v6
	v_and_b32_e32 v11, 0xffff0000, v6
	v_lshlrev_b32_e32 v6, 16, v7
	v_and_b32_e32 v7, 0xffff0000, v7
	v_lshlrev_b32_e32 v12, 16, v8
	v_and_b32_e32 v13, 0xffff0000, v8
	v_lshlrev_b32_e32 v8, 16, v9
	v_and_b32_e32 v9, 0xffff0000, v9
	v_add_co_u32_e32 v4, vcc, 0x1000, v4
	s_waitcnt vmcnt(7)
	s_nop 1
	v_mov_b32_e32 v0, v92
	v_mov_b32_e32 v1, v93
	v_mov_b32_e32 v2, v94
	v_mov_b32_e32 v3, v95
	v_lshlrev_b32_e32 v14, 16, v0
	v_and_b32_e32 v15, 0xffff0000, v0
	v_lshlrev_b32_e32 v0, 16, v1
	v_and_b32_e32 v1, 0xffff0000, v1
	v_lshlrev_b32_e32 v16, 16, v2
	v_and_b32_e32 v17, 0xffff0000, v2
	v_lshlrev_b32_e32 v2, 16, v3
	v_and_b32_e32 v3, 0xffff0000, v3
	v_mul_f32_e32 v18, 0xbfb8aa3b, v14
	v_mul_f32_e32 v19, 0xbfb8aa3b, v15
	v_mul_f32_e32 v20, 0xbfb8aa3b, v0
	v_mul_f32_e32 v21, 0xbfb8aa3b, v1
	v_mul_f32_e32 v22, 0xbfb8aa3b, v16
	v_mul_f32_e32 v23, 0xbfb8aa3b, v17
	v_mul_f32_e32 v24, 0xbfb8aa3b, v2
	v_mul_f32_e32 v25, 0xbfb8aa3b, v3
	v_exp_f32_e32 v18, v18
	v_exp_f32_e32 v19, v19
	v_exp_f32_e32 v20, v20
	v_exp_f32_e32 v21, v21
	v_exp_f32_e32 v22, v22
	v_exp_f32_e32 v23, v23
	v_exp_f32_e32 v24, v24
	v_exp_f32_e32 v25, v25
	v_add_f32_e32 v18, 1.0, v18
	v_add_f32_e32 v19, 1.0, v19
	v_add_f32_e32 v20, 1.0, v20
	v_add_f32_e32 v21, 1.0, v21
	v_add_f32_e32 v22, 1.0, v22
	v_add_f32_e32 v23, 1.0, v23
	v_add_f32_e32 v24, 1.0, v24
	v_add_f32_e32 v25, 1.0, v25
	v_rcp_f32_e32 v18, v18
	v_rcp_f32_e32 v19, v19
	v_rcp_f32_e32 v20, v20
	v_rcp_f32_e32 v21, v21
	v_rcp_f32_e32 v22, v22
	v_rcp_f32_e32 v23, v23
	v_rcp_f32_e32 v24, v24
	v_rcp_f32_e32 v25, v25
	v_pk_mul_f32 v[14:15], v[18:19], v[14:15]
	v_pk_mul_f32 v[0:1], v[20:21], v[0:1]
	v_pk_mul_f32 v[16:17], v[22:23], v[16:17]
	v_pk_mul_f32 v[2:3], v[24:25], v[2:3]
	v_pk_mul_f32 v[10:11], v[14:15], v[10:11]
	v_pk_mul_f32 v[6:7], v[0:1], v[6:7]
	v_pk_mul_f32 v[12:13], v[16:17], v[12:13]
	v_pk_mul_f32 v[8:9], v[2:3], v[8:9]
	v_addc_co_u32_e32 v5, vcc, 0, v5, vcc
	v_cvt_pk_bf16_f32 v0, v10, v11
	v_cvt_pk_bf16_f32 v1, v6, v7
	v_cvt_pk_bf16_f32 v2, v12, v13
	v_cvt_pk_bf16_f32 v3, v8, v9
	global_store_dwordx4 v[4:5], v[0:3], off
	s_cbranch_scc1 .LBB0_369
